# phase0: batch the serialized loads in silu staging and adaLN k-loops
# baseline (speedup 1.0000x reference)
.LBB0_10:
	s_load_dwordx16 s[36:51], s[0:1], 0x40
	v_lshlrev_b32_e32 v164, 2, v146
	v_add_u32_e32 v1, 0, v164
	s_mov_b64 s[0:1], 0
	s_movk_i32 s3, 0x400
	s_movk_i32 s4, 0x3ff
	v_mov_b32_e32 v4, s59
	v_mov_b32_e32 v5, s61
	v_mov_b32_e32 v6, s58
	v_mov_b32_e32 v7, s60
	v_mov_b32_e32 v3, 0
	s_movk_i32 s5, 0x21ff
	v_mov_b32_e32 v8, v146
	global_load_dword v10, v164, s[60:61]
	global_load_dword v11, v164, s[60:61] offset:2048
	global_load_dword v12, v164, s[58:59]
	global_load_dword v13, v164, s[58:59] offset:2048
	v_add_u32_e32 v2, 0x1000, v164
	global_load_dword v14, v2, s[58:59]
	global_load_dword v15, v2, s[58:59] offset:2048
	v_add_u32_e32 v2, 0x2000, v164
	global_load_dword v16, v2, s[58:59]
	global_load_dword v17, v2, s[58:59] offset:2048
	v_add_u32_e32 v2, 0x3000, v164
	global_load_dword v18, v2, s[58:59]
	global_load_dword v19, v2, s[58:59] offset:2048
	v_add_u32_e32 v2, 0x4000, v164
	global_load_dword v20, v2, s[58:59]
	global_load_dword v21, v2, s[58:59] offset:2048
	v_add_u32_e32 v2, 0x5000, v164
	global_load_dword v22, v2, s[58:59]
	global_load_dword v23, v2, s[58:59] offset:2048
	v_add_u32_e32 v2, 0x6000, v164
	global_load_dword v24, v2, s[58:59]
	global_load_dword v25, v2, s[58:59] offset:2048
	v_add_u32_e32 v2, 0x7000, v164
	global_load_dword v26, v2, s[58:59]
	global_load_dword v27, v2, s[58:59] offset:2048
	s_waitcnt vmcnt(16)
	v_mul_f32_e32 v28, 0xbfb8aa3b, v10
	v_mul_f32_e32 v29, 0xbfb8aa3b, v11
	v_exp_f32_e32 v28, v28
	v_exp_f32_e32 v29, v29
	v_add_f32_e32 v28, 1.0, v28
	v_add_f32_e32 v29, 1.0, v29
	v_rcp_f32_e32 v28, v28
	v_rcp_f32_e32 v29, v29
	v_mul_f32_e32 v28, v10, v28
	v_mul_f32_e32 v29, v11, v29
	ds_write_b32 v1, v28
	ds_write_b32 v1, v29 offset:2048
	s_waitcnt vmcnt(14)
	v_mul_f32_e32 v28, 0xbfb8aa3b, v12
	v_mul_f32_e32 v29, 0xbfb8aa3b, v13
	v_exp_f32_e32 v28, v28
	v_exp_f32_e32 v29, v29
	v_add_f32_e32 v28, 1.0, v28
	v_add_f32_e32 v29, 1.0, v29
	v_rcp_f32_e32 v28, v28
	v_rcp_f32_e32 v29, v29
	v_mul_f32_e32 v28, v12, v28
	v_mul_f32_e32 v29, v13, v29
	ds_write_b32 v1, v28 offset:4096
	ds_write_b32 v1, v29 offset:6144
	s_waitcnt vmcnt(12)
	v_mul_f32_e32 v28, 0xbfb8aa3b, v14
	v_mul_f32_e32 v29, 0xbfb8aa3b, v15
	v_exp_f32_e32 v28, v28
	v_exp_f32_e32 v29, v29
	v_add_f32_e32 v28, 1.0, v28
	v_add_f32_e32 v29, 1.0, v29
	v_rcp_f32_e32 v28, v28
	v_rcp_f32_e32 v29, v29
	v_mul_f32_e32 v28, v14, v28
	v_mul_f32_e32 v29, v15, v29
	ds_write_b32 v1, v28 offset:8192
	ds_write_b32 v1, v29 offset:10240
	s_waitcnt vmcnt(10)
	v_mul_f32_e32 v28, 0xbfb8aa3b, v16
	v_mul_f32_e32 v29, 0xbfb8aa3b, v17
	v_exp_f32_e32 v28, v28
	v_exp_f32_e32 v29, v29
	v_add_f32_e32 v28, 1.0, v28
	v_add_f32_e32 v29, 1.0, v29
	v_rcp_f32_e32 v28, v28
	v_rcp_f32_e32 v29, v29
	v_mul_f32_e32 v28, v16, v28
	v_mul_f32_e32 v29, v17, v29
	ds_write_b32 v1, v28 offset:12288
	ds_write_b32 v1, v29 offset:14336
	s_waitcnt vmcnt(8)
	v_mul_f32_e32 v28, 0xbfb8aa3b, v18
	v_mul_f32_e32 v29, 0xbfb8aa3b, v19
	v_exp_f32_e32 v28, v28
	v_exp_f32_e32 v29, v29
	v_add_f32_e32 v28, 1.0, v28
	v_add_f32_e32 v29, 1.0, v29
	v_rcp_f32_e32 v28, v28
	v_rcp_f32_e32 v29, v29
	v_mul_f32_e32 v28, v18, v28
	v_mul_f32_e32 v29, v19, v29
	ds_write_b32 v1, v28 offset:16384
	ds_write_b32 v1, v29 offset:18432
	s_waitcnt vmcnt(6)
	v_mul_f32_e32 v28, 0xbfb8aa3b, v20
	v_mul_f32_e32 v29, 0xbfb8aa3b, v21
	v_exp_f32_e32 v28, v28
	v_exp_f32_e32 v29, v29
	v_add_f32_e32 v28, 1.0, v28
	v_add_f32_e32 v29, 1.0, v29
	v_rcp_f32_e32 v28, v28
	v_rcp_f32_e32 v29, v29
	v_mul_f32_e32 v28, v20, v28
	v_mul_f32_e32 v29, v21, v29
	ds_write_b32 v1, v28 offset:20480
	ds_write_b32 v1, v29 offset:22528
	s_waitcnt vmcnt(4)
	v_mul_f32_e32 v28, 0xbfb8aa3b, v22
	v_mul_f32_e32 v29, 0xbfb8aa3b, v23
	v_exp_f32_e32 v28, v28
	v_exp_f32_e32 v29, v29
	v_add_f32_e32 v28, 1.0, v28
	v_add_f32_e32 v29, 1.0, v29
	v_rcp_f32_e32 v28, v28
	v_rcp_f32_e32 v29, v29
	v_mul_f32_e32 v28, v22, v28
	v_mul_f32_e32 v29, v23, v29
	ds_write_b32 v1, v28 offset:24576
	ds_write_b32 v1, v29 offset:26624
	s_waitcnt vmcnt(2)
	v_mul_f32_e32 v28, 0xbfb8aa3b, v24
	v_mul_f32_e32 v29, 0xbfb8aa3b, v25
	v_exp_f32_e32 v28, v28
	v_exp_f32_e32 v29, v29
	v_add_f32_e32 v28, 1.0, v28
	v_add_f32_e32 v29, 1.0, v29
	v_rcp_f32_e32 v28, v28
	v_rcp_f32_e32 v29, v29
	v_mul_f32_e32 v28, v24, v28
	v_mul_f32_e32 v29, v25, v29
	ds_write_b32 v1, v28 offset:28672
	ds_write_b32 v1, v29 offset:30720
	s_waitcnt vmcnt(0)
	v_mul_f32_e32 v28, 0xbfb8aa3b, v26
	v_mul_f32_e32 v29, 0xbfb8aa3b, v27
	v_exp_f32_e32 v28, v28
	v_exp_f32_e32 v29, v29
	v_add_f32_e32 v28, 1.0, v28
	v_add_f32_e32 v29, 1.0, v29
	v_rcp_f32_e32 v28, v28
	v_rcp_f32_e32 v29, v29
	v_mul_f32_e32 v28, v26, v28
	v_mul_f32_e32 v29, v27, v29
	ds_write_b32 v1, v28 offset:32768
	ds_write_b32 v1, v29 offset:34816
	s_or_b64 exec, exec, s[0:1]
	s_add_u32 s60, s34, 0x314c000
	s_addc_u32 s61, s35, 0
	s_cmpk_lt_i32 s2, 0x100
	s_cselect_b64 s[10:11], -1, 0
	s_cmpk_gt_i32 s2, 0xff
	s_mov_b32 s0, s68
	s_waitcnt lgkmcnt(0)
	s_barrier
	s_cbranch_scc1 .LBB0_22
	v_mul_u32_u24_e32 v1, 0x1c72, v146
	v_lshrrev_b32_e32 v2, 16, v1
	v_mul_lo_u16_e32 v1, 9, v2
	v_sub_u16_e32 v3, v146, v1
	v_mul_u32_u24_e32 v1, 0x71d, v146
	v_lshrrev_b32_e32 v5, 16, v1
	v_mul_lo_u16_e32 v1, 36, v5
	v_sub_u16_e32 v1, v146, v1
	s_movk_i32 s0, 0x1f8
	v_and_b32_e32 v7, 3, v1
	v_cmp_gt_u32_e32 vcc, s0, v146
	s_movk_i32 s0, 0x144
	v_lshrrev_b32_e32 v6, 2, v1
	v_lshlrev_b32_e32 v8, 2, v1
	v_lshl_or_b32 v1, v5, 2, v7
	v_mul_u32_u24_e32 v5, 0x90, v5
	v_subrev_u32_e32 v50, 56, v2
	v_lshl_add_u32 v51, v2, 2, 0
	s_mov_b32 s1, 0x1c71c71d
	v_lshlrev_b16_e32 v2, 2, v3
	v_cmp_gt_u32_e64 s[4:5], s0, v146
	v_add3_u32 v42, 0, v8, v5
	s_mov_b32 s0, 0x9000
	v_mul_hi_u32 v5, v146, s1
	v_lshlrev_b32_e32 v2, 2, v2
	v_mov_b32_e32 v3, 0
	v_mul_u32_u24_e32 v4, 0x90, v146
	v_mul_u32_u24_e32 v6, 0x2400, v6
	v_mad_u64_u32 v[2:3], s[0:1], v5, s0, v[2:3]
	v_add_u32_e32 v43, 0x9000, v42
	v_add_u32_e32 v44, 0x19230, v42
	v_add_u32_e32 v45, 0x19740, v42
	v_add_u32_e32 v46, 0x19c50, v42
	v_add_u32_e32 v47, 0x1a160, v42
	v_add_u32_e32 v48, 0x1a670, v42
	v_or_b32_e32 v49, v1, v6
	v_lshl_add_u64 v[38:39], s[62:63], 0, v[2:3]
	s_mul_i32 s6, s2, 36
	s_mul_i32 s3, s68, 36
	s_mov_b64 s[8:9], 0x1f8000
	s_movk_i32 s16, 0x3c7
	v_add_u32_e32 v52, 0, v4
	s_mov_b32 s17, s2
	s_branch .LBB0_15

.LBB0_15:
	s_and_saveexec_b64 s[12:13], vcc
	s_cbranch_execz .LBB0_19
	s_ashr_i32 s7, s6, 31
	v_mov_b32_e32 v14, 0
	v_lshl_add_u64 v[40:41], s[6:7], 2, v[38:39]
	s_mov_b64 s[14:15], 0
	v_mov_b32_e32 v53, v51
	v_mov_b32_e32 v54, v50
	v_mov_b32_e32 v15, v14
	v_mov_b32_e32 v16, v14
	v_mov_b32_e32 v17, v14
	v_mov_b32_e32 v34, v14
	v_mov_b32_e32 v35, v14
	v_mov_b32_e32 v36, v14
	v_mov_b32_e32 v37, v14
	v_mov_b32_e32 v30, v14
	v_mov_b32_e32 v31, v14
	v_mov_b32_e32 v32, v14
	v_mov_b32_e32 v33, v14
	v_mov_b32_e32 v26, v14
	v_mov_b32_e32 v27, v14
	v_mov_b32_e32 v28, v14
	v_mov_b32_e32 v29, v14
	v_mov_b32_e32 v22, v14
	v_mov_b32_e32 v23, v14
	v_mov_b32_e32 v24, v14
	v_mov_b32_e32 v25, v14
	v_mov_b32_e32 v18, v14
	v_mov_b32_e32 v19, v14
	v_mov_b32_e32 v20, v14
	v_mov_b32_e32 v21, v14
	v_mov_b32_e32 v10, v14
	v_mov_b32_e32 v11, v14
	v_mov_b32_e32 v12, v14
	v_mov_b32_e32 v13, v14
	v_mov_b32_e32 v6, v14
	v_mov_b32_e32 v7, v14
	v_mov_b32_e32 v8, v14
	v_mov_b32_e32 v9, v14
	v_mov_b32_e32 v2, v14
	v_mov_b32_e32 v3, v14
	v_mov_b32_e32 v4, v14
	v_mov_b32_e32 v5, v14
	v_add_u32_e32 v78, 56, v50
	s_mov_b32 s18, 0x2370000
	s_mov_b32 s19, 0
	v_cmp_gt_u32_e64 s[0:1], 16, v78
	v_lshl_add_u64 v[78:79], v[40:41], 0, s[18:19]
	s_nop 1
	s_and_saveexec_b64 s[14:15], s[0:1]
	global_load_dwordx4 v[156:159], v[78:79], off
	s_mov_b64 exec, s[14:15]
	global_load_dwordx4 v[80:83], v[40:41], off
	v_lshl_add_u64 v[40:41], v[40:41], 0, s[8:9]
	global_load_dwordx4 v[84:87], v[40:41], off
	v_lshl_add_u64 v[40:41], v[40:41], 0, s[8:9]
	global_load_dwordx4 v[88:91], v[40:41], off
	v_lshl_add_u64 v[40:41], v[40:41], 0, s[8:9]
	global_load_dwordx4 v[92:95], v[40:41], off
	v_lshl_add_u64 v[40:41], v[40:41], 0, s[8:9]
	global_load_dwordx4 v[96:99], v[40:41], off
	v_lshl_add_u64 v[40:41], v[40:41], 0, s[8:9]
	global_load_dwordx4 v[100:103], v[40:41], off
	v_lshl_add_u64 v[40:41], v[40:41], 0, s[8:9]
	global_load_dwordx4 v[104:107], v[40:41], off
	v_lshl_add_u64 v[40:41], v[40:41], 0, s[8:9]
	global_load_dwordx4 v[108:111], v[40:41], off
	v_lshl_add_u64 v[40:41], v[40:41], 0, s[8:9]
	global_load_dwordx4 v[112:115], v[40:41], off
	v_lshl_add_u64 v[40:41], v[40:41], 0, s[8:9]
	global_load_dwordx4 v[116:119], v[40:41], off
	v_lshl_add_u64 v[40:41], v[40:41], 0, s[8:9]
	global_load_dwordx4 v[120:123], v[40:41], off
	v_lshl_add_u64 v[40:41], v[40:41], 0, s[8:9]
	global_load_dwordx4 v[124:127], v[40:41], off
	v_lshl_add_u64 v[40:41], v[40:41], 0, s[8:9]
	global_load_dwordx4 v[128:131], v[40:41], off
	v_lshl_add_u64 v[40:41], v[40:41], 0, s[8:9]
	global_load_dwordx4 v[132:135], v[40:41], off
	v_lshl_add_u64 v[40:41], v[40:41], 0, s[8:9]
	global_load_dwordx4 v[136:139], v[40:41], off
	v_lshl_add_u64 v[40:41], v[40:41], 0, s[8:9]
	global_load_dwordx4 v[140:143], v[40:41], off
	v_lshl_add_u64 v[40:41], v[40:41], 0, s[8:9]
	global_load_dwordx4 v[148:151], v[40:41], off
	v_lshl_add_u64 v[40:41], v[40:41], 0, s[8:9]
	global_load_dwordx4 v[152:155], v[40:41], off
	ds_read2st64_b32 v[60:61], v53 offset1:16
	ds_read2st64_b32 v[62:63], v53 offset0:32 offset1:48
	ds_read2st64_b32 v[64:65], v53 offset0:64 offset1:80
	ds_read2st64_b32 v[66:67], v53 offset0:96 offset1:112
	ds_read_b32 v68, v53 offset:32768
	s_waitcnt lgkmcnt(4)
	v_mov_b32_e32 v70, v61
	s_waitcnt lgkmcnt(3)
	v_mov_b32_e32 v72, v63
	s_waitcnt lgkmcnt(2)
	v_mov_b32_e32 v74, v65
	s_waitcnt lgkmcnt(1)
	v_mov_b32_e32 v76, v67
	v_add_u32_e32 v53, 0xe0, v53
	s_waitcnt vmcnt(17)
	v_pk_fma_f32 v[14:15], v[60:61], v[80:81], v[14:15] op_sel_hi:[0,1,1]
	v_pk_fma_f32 v[16:17], v[60:61], v[82:83], v[16:17] op_sel_hi:[0,1,1]
	v_pk_fma_f32 v[34:35], v[80:81], v[70:71], v[34:35] op_sel_hi:[1,0,1]
	v_pk_fma_f32 v[36:37], v[82:83], v[70:71], v[36:37] op_sel_hi:[1,0,1]
	v_pk_fma_f32 v[30:31], v[80:81], v[62:63], v[30:31] op_sel_hi:[1,0,1]
	v_pk_fma_f32 v[32:33], v[82:83], v[62:63], v[32:33] op_sel_hi:[1,0,1]
	v_pk_fma_f32 v[26:27], v[80:81], v[72:73], v[26:27] op_sel_hi:[1,0,1]
	v_pk_fma_f32 v[28:29], v[82:83], v[72:73], v[28:29] op_sel_hi:[1,0,1]
	v_pk_fma_f32 v[22:23], v[80:81], v[64:65], v[22:23] op_sel_hi:[1,0,1]
	v_pk_fma_f32 v[24:25], v[82:83], v[64:65], v[24:25] op_sel_hi:[1,0,1]
	v_pk_fma_f32 v[18:19], v[80:81], v[74:75], v[18:19] op_sel_hi:[1,0,1]
	v_pk_fma_f32 v[20:21], v[82:83], v[74:75], v[20:21] op_sel_hi:[1,0,1]
	v_pk_fma_f32 v[10:11], v[80:81], v[66:67], v[10:11] op_sel_hi:[1,0,1]
	v_pk_fma_f32 v[12:13], v[82:83], v[66:67], v[12:13] op_sel_hi:[1,0,1]
	v_pk_fma_f32 v[6:7], v[80:81], v[76:77], v[6:7] op_sel_hi:[1,0,1]
	v_pk_fma_f32 v[8:9], v[82:83], v[76:77], v[8:9] op_sel_hi:[1,0,1]
	s_waitcnt lgkmcnt(0)
	v_pk_fma_f32 v[2:3], v[80:81], v[68:69], v[2:3] op_sel_hi:[1,0,1]
	v_pk_fma_f32 v[4:5], v[82:83], v[68:69], v[4:5] op_sel_hi:[1,0,1]
	ds_read2st64_b32 v[60:61], v53 offset1:16
	ds_read2st64_b32 v[62:63], v53 offset0:32 offset1:48
	ds_read2st64_b32 v[64:65], v53 offset0:64 offset1:80
	ds_read2st64_b32 v[66:67], v53 offset0:96 offset1:112
	ds_read_b32 v68, v53 offset:32768
	s_waitcnt lgkmcnt(4)
	v_mov_b32_e32 v70, v61
	s_waitcnt lgkmcnt(3)
	v_mov_b32_e32 v72, v63
	s_waitcnt lgkmcnt(2)
	v_mov_b32_e32 v74, v65
	s_waitcnt lgkmcnt(1)
	v_mov_b32_e32 v76, v67
	v_add_u32_e32 v53, 0xe0, v53
	s_waitcnt vmcnt(16)
	v_pk_fma_f32 v[14:15], v[60:61], v[84:85], v[14:15] op_sel_hi:[0,1,1]
	v_pk_fma_f32 v[16:17], v[60:61], v[86:87], v[16:17] op_sel_hi:[0,1,1]
	v_pk_fma_f32 v[34:35], v[84:85], v[70:71], v[34:35] op_sel_hi:[1,0,1]
	v_pk_fma_f32 v[36:37], v[86:87], v[70:71], v[36:37] op_sel_hi:[1,0,1]
	v_pk_fma_f32 v[30:31], v[84:85], v[62:63], v[30:31] op_sel_hi:[1,0,1]
	v_pk_fma_f32 v[32:33], v[86:87], v[62:63], v[32:33] op_sel_hi:[1,0,1]
	v_pk_fma_f32 v[26:27], v[84:85], v[72:73], v[26:27] op_sel_hi:[1,0,1]
	v_pk_fma_f32 v[28:29], v[86:87], v[72:73], v[28:29] op_sel_hi:[1,0,1]
	v_pk_fma_f32 v[22:23], v[84:85], v[64:65], v[22:23] op_sel_hi:[1,0,1]
	v_pk_fma_f32 v[24:25], v[86:87], v[64:65], v[24:25] op_sel_hi:[1,0,1]
	v_pk_fma_f32 v[18:19], v[84:85], v[74:75], v[18:19] op_sel_hi:[1,0,1]
	v_pk_fma_f32 v[20:21], v[86:87], v[74:75], v[20:21] op_sel_hi:[1,0,1]
	v_pk_fma_f32 v[10:11], v[84:85], v[66:67], v[10:11] op_sel_hi:[1,0,1]
	v_pk_fma_f32 v[12:13], v[86:87], v[66:67], v[12:13] op_sel_hi:[1,0,1]
	v_pk_fma_f32 v[6:7], v[84:85], v[76:77], v[6:7] op_sel_hi:[1,0,1]
	v_pk_fma_f32 v[8:9], v[86:87], v[76:77], v[8:9] op_sel_hi:[1,0,1]
	s_waitcnt lgkmcnt(0)
	v_pk_fma_f32 v[2:3], v[84:85], v[68:69], v[2:3] op_sel_hi:[1,0,1]
	v_pk_fma_f32 v[4:5], v[86:87], v[68:69], v[4:5] op_sel_hi:[1,0,1]
	ds_read2st64_b32 v[60:61], v53 offset1:16
	ds_read2st64_b32 v[62:63], v53 offset0:32 offset1:48
	ds_read2st64_b32 v[64:65], v53 offset0:64 offset1:80
	ds_read2st64_b32 v[66:67], v53 offset0:96 offset1:112
	ds_read_b32 v68, v53 offset:32768
	s_waitcnt lgkmcnt(4)
	v_mov_b32_e32 v70, v61
	s_waitcnt lgkmcnt(3)
	v_mov_b32_e32 v72, v63
	s_waitcnt lgkmcnt(2)
	v_mov_b32_e32 v74, v65
	s_waitcnt lgkmcnt(1)
	v_mov_b32_e32 v76, v67
	v_add_u32_e32 v53, 0xe0, v53
	s_waitcnt vmcnt(15)
	v_pk_fma_f32 v[14:15], v[60:61], v[88:89], v[14:15] op_sel_hi:[0,1,1]
	v_pk_fma_f32 v[16:17], v[60:61], v[90:91], v[16:17] op_sel_hi:[0,1,1]
	v_pk_fma_f32 v[34:35], v[88:89], v[70:71], v[34:35] op_sel_hi:[1,0,1]
	v_pk_fma_f32 v[36:37], v[90:91], v[70:71], v[36:37] op_sel_hi:[1,0,1]
	v_pk_fma_f32 v[30:31], v[88:89], v[62:63], v[30:31] op_sel_hi:[1,0,1]
	v_pk_fma_f32 v[32:33], v[90:91], v[62:63], v[32:33] op_sel_hi:[1,0,1]
	v_pk_fma_f32 v[26:27], v[88:89], v[72:73], v[26:27] op_sel_hi:[1,0,1]
	v_pk_fma_f32 v[28:29], v[90:91], v[72:73], v[28:29] op_sel_hi:[1,0,1]
	v_pk_fma_f32 v[22:23], v[88:89], v[64:65], v[22:23] op_sel_hi:[1,0,1]
	v_pk_fma_f32 v[24:25], v[90:91], v[64:65], v[24:25] op_sel_hi:[1,0,1]
	v_pk_fma_f32 v[18:19], v[88:89], v[74:75], v[18:19] op_sel_hi:[1,0,1]
	v_pk_fma_f32 v[20:21], v[90:91], v[74:75], v[20:21] op_sel_hi:[1,0,1]
	v_pk_fma_f32 v[10:11], v[88:89], v[66:67], v[10:11] op_sel_hi:[1,0,1]
	v_pk_fma_f32 v[12:13], v[90:91], v[66:67], v[12:13] op_sel_hi:[1,0,1]
	v_pk_fma_f32 v[6:7], v[88:89], v[76:77], v[6:7] op_sel_hi:[1,0,1]
	v_pk_fma_f32 v[8:9], v[90:91], v[76:77], v[8:9] op_sel_hi:[1,0,1]
	s_waitcnt lgkmcnt(0)
	v_pk_fma_f32 v[2:3], v[88:89], v[68:69], v[2:3] op_sel_hi:[1,0,1]
	v_pk_fma_f32 v[4:5], v[90:91], v[68:69], v[4:5] op_sel_hi:[1,0,1]
	ds_read2st64_b32 v[60:61], v53 offset1:16
	ds_read2st64_b32 v[62:63], v53 offset0:32 offset1:48
	ds_read2st64_b32 v[64:65], v53 offset0:64 offset1:80
	ds_read2st64_b32 v[66:67], v53 offset0:96 offset1:112
	ds_read_b32 v68, v53 offset:32768
	s_waitcnt lgkmcnt(4)
	v_mov_b32_e32 v70, v61
	s_waitcnt lgkmcnt(3)
	v_mov_b32_e32 v72, v63
	s_waitcnt lgkmcnt(2)
	v_mov_b32_e32 v74, v65
	s_waitcnt lgkmcnt(1)
	v_mov_b32_e32 v76, v67
	v_add_u32_e32 v53, 0xe0, v53
	s_waitcnt vmcnt(14)
	v_pk_fma_f32 v[14:15], v[60:61], v[92:93], v[14:15] op_sel_hi:[0,1,1]
	v_pk_fma_f32 v[16:17], v[60:61], v[94:95], v[16:17] op_sel_hi:[0,1,1]
	v_pk_fma_f32 v[34:35], v[92:93], v[70:71], v[34:35] op_sel_hi:[1,0,1]
	v_pk_fma_f32 v[36:37], v[94:95], v[70:71], v[36:37] op_sel_hi:[1,0,1]
	v_pk_fma_f32 v[30:31], v[92:93], v[62:63], v[30:31] op_sel_hi:[1,0,1]
	v_pk_fma_f32 v[32:33], v[94:95], v[62:63], v[32:33] op_sel_hi:[1,0,1]
	v_pk_fma_f32 v[26:27], v[92:93], v[72:73], v[26:27] op_sel_hi:[1,0,1]
	v_pk_fma_f32 v[28:29], v[94:95], v[72:73], v[28:29] op_sel_hi:[1,0,1]
	v_pk_fma_f32 v[22:23], v[92:93], v[64:65], v[22:23] op_sel_hi:[1,0,1]
	v_pk_fma_f32 v[24:25], v[94:95], v[64:65], v[24:25] op_sel_hi:[1,0,1]
	v_pk_fma_f32 v[18:19], v[92:93], v[74:75], v[18:19] op_sel_hi:[1,0,1]
	v_pk_fma_f32 v[20:21], v[94:95], v[74:75], v[20:21] op_sel_hi:[1,0,1]
	v_pk_fma_f32 v[10:11], v[92:93], v[66:67], v[10:11] op_sel_hi:[1,0,1]
	v_pk_fma_f32 v[12:13], v[94:95], v[66:67], v[12:13] op_sel_hi:[1,0,1]
	v_pk_fma_f32 v[6:7], v[92:93], v[76:77], v[6:7] op_sel_hi:[1,0,1]
	v_pk_fma_f32 v[8:9], v[94:95], v[76:77], v[8:9] op_sel_hi:[1,0,1]
	s_waitcnt lgkmcnt(0)
	v_pk_fma_f32 v[2:3], v[92:93], v[68:69], v[2:3] op_sel_hi:[1,0,1]
	v_pk_fma_f32 v[4:5], v[94:95], v[68:69], v[4:5] op_sel_hi:[1,0,1]
	ds_read2st64_b32 v[60:61], v53 offset1:16
	ds_read2st64_b32 v[62:63], v53 offset0:32 offset1:48
	ds_read2st64_b32 v[64:65], v53 offset0:64 offset1:80
	ds_read2st64_b32 v[66:67], v53 offset0:96 offset1:112
	ds_read_b32 v68, v53 offset:32768
	s_waitcnt lgkmcnt(4)
	v_mov_b32_e32 v70, v61
	s_waitcnt lgkmcnt(3)
	v_mov_b32_e32 v72, v63
	s_waitcnt lgkmcnt(2)
	v_mov_b32_e32 v74, v65
	s_waitcnt lgkmcnt(1)
	v_mov_b32_e32 v76, v67
	v_add_u32_e32 v53, 0xe0, v53
	s_waitcnt vmcnt(13)
	v_pk_fma_f32 v[14:15], v[60:61], v[96:97], v[14:15] op_sel_hi:[0,1,1]
	v_pk_fma_f32 v[16:17], v[60:61], v[98:99], v[16:17] op_sel_hi:[0,1,1]
	v_pk_fma_f32 v[34:35], v[96:97], v[70:71], v[34:35] op_sel_hi:[1,0,1]
	v_pk_fma_f32 v[36:37], v[98:99], v[70:71], v[36:37] op_sel_hi:[1,0,1]
	v_pk_fma_f32 v[30:31], v[96:97], v[62:63], v[30:31] op_sel_hi:[1,0,1]
	v_pk_fma_f32 v[32:33], v[98:99], v[62:63], v[32:33] op_sel_hi:[1,0,1]
	v_pk_fma_f32 v[26:27], v[96:97], v[72:73], v[26:27] op_sel_hi:[1,0,1]
	v_pk_fma_f32 v[28:29], v[98:99], v[72:73], v[28:29] op_sel_hi:[1,0,1]
	v_pk_fma_f32 v[22:23], v[96:97], v[64:65], v[22:23] op_sel_hi:[1,0,1]
	v_pk_fma_f32 v[24:25], v[98:99], v[64:65], v[24:25] op_sel_hi:[1,0,1]
	v_pk_fma_f32 v[18:19], v[96:97], v[74:75], v[18:19] op_sel_hi:[1,0,1]
	v_pk_fma_f32 v[20:21], v[98:99], v[74:75], v[20:21] op_sel_hi:[1,0,1]
	v_pk_fma_f32 v[10:11], v[96:97], v[66:67], v[10:11] op_sel_hi:[1,0,1]
	v_pk_fma_f32 v[12:13], v[98:99], v[66:67], v[12:13] op_sel_hi:[1,0,1]
	v_pk_fma_f32 v[6:7], v[96:97], v[76:77], v[6:7] op_sel_hi:[1,0,1]
	v_pk_fma_f32 v[8:9], v[98:99], v[76:77], v[8:9] op_sel_hi:[1,0,1]
	s_waitcnt lgkmcnt(0)
	v_pk_fma_f32 v[2:3], v[96:97], v[68:69], v[2:3] op_sel_hi:[1,0,1]
	v_pk_fma_f32 v[4:5], v[98:99], v[68:69], v[4:5] op_sel_hi:[1,0,1]
	ds_read2st64_b32 v[60:61], v53 offset1:16
	ds_read2st64_b32 v[62:63], v53 offset0:32 offset1:48
	ds_read2st64_b32 v[64:65], v53 offset0:64 offset1:80
	ds_read2st64_b32 v[66:67], v53 offset0:96 offset1:112
	ds_read_b32 v68, v53 offset:32768
	s_waitcnt lgkmcnt(4)
	v_mov_b32_e32 v70, v61
	s_waitcnt lgkmcnt(3)
	v_mov_b32_e32 v72, v63
	s_waitcnt lgkmcnt(2)
	v_mov_b32_e32 v74, v65
	s_waitcnt lgkmcnt(1)
	v_mov_b32_e32 v76, v67
	v_add_u32_e32 v53, 0xe0, v53
	s_waitcnt vmcnt(12)
	v_pk_fma_f32 v[14:15], v[60:61], v[100:101], v[14:15] op_sel_hi:[0,1,1]
	v_pk_fma_f32 v[16:17], v[60:61], v[102:103], v[16:17] op_sel_hi:[0,1,1]
	v_pk_fma_f32 v[34:35], v[100:101], v[70:71], v[34:35] op_sel_hi:[1,0,1]
	v_pk_fma_f32 v[36:37], v[102:103], v[70:71], v[36:37] op_sel_hi:[1,0,1]
	v_pk_fma_f32 v[30:31], v[100:101], v[62:63], v[30:31] op_sel_hi:[1,0,1]
	v_pk_fma_f32 v[32:33], v[102:103], v[62:63], v[32:33] op_sel_hi:[1,0,1]
	v_pk_fma_f32 v[26:27], v[100:101], v[72:73], v[26:27] op_sel_hi:[1,0,1]
	v_pk_fma_f32 v[28:29], v[102:103], v[72:73], v[28:29] op_sel_hi:[1,0,1]
	v_pk_fma_f32 v[22:23], v[100:101], v[64:65], v[22:23] op_sel_hi:[1,0,1]
	v_pk_fma_f32 v[24:25], v[102:103], v[64:65], v[24:25] op_sel_hi:[1,0,1]
	v_pk_fma_f32 v[18:19], v[100:101], v[74:75], v[18:19] op_sel_hi:[1,0,1]
	v_pk_fma_f32 v[20:21], v[102:103], v[74:75], v[20:21] op_sel_hi:[1,0,1]
	v_pk_fma_f32 v[10:11], v[100:101], v[66:67], v[10:11] op_sel_hi:[1,0,1]
	v_pk_fma_f32 v[12:13], v[102:103], v[66:67], v[12:13] op_sel_hi:[1,0,1]
	v_pk_fma_f32 v[6:7], v[100:101], v[76:77], v[6:7] op_sel_hi:[1,0,1]
	v_pk_fma_f32 v[8:9], v[102:103], v[76:77], v[8:9] op_sel_hi:[1,0,1]
	s_waitcnt lgkmcnt(0)
	v_pk_fma_f32 v[2:3], v[100:101], v[68:69], v[2:3] op_sel_hi:[1,0,1]
	v_pk_fma_f32 v[4:5], v[102:103], v[68:69], v[4:5] op_sel_hi:[1,0,1]
	ds_read2st64_b32 v[60:61], v53 offset1:16
	ds_read2st64_b32 v[62:63], v53 offset0:32 offset1:48
	ds_read2st64_b32 v[64:65], v53 offset0:64 offset1:80
	ds_read2st64_b32 v[66:67], v53 offset0:96 offset1:112
	ds_read_b32 v68, v53 offset:32768
	s_waitcnt lgkmcnt(4)
	v_mov_b32_e32 v70, v61
	s_waitcnt lgkmcnt(3)
	v_mov_b32_e32 v72, v63
	s_waitcnt lgkmcnt(2)
	v_mov_b32_e32 v74, v65
	s_waitcnt lgkmcnt(1)
	v_mov_b32_e32 v76, v67
	v_add_u32_e32 v53, 0xe0, v53
	s_waitcnt vmcnt(11)
	v_pk_fma_f32 v[14:15], v[60:61], v[104:105], v[14:15] op_sel_hi:[0,1,1]
	v_pk_fma_f32 v[16:17], v[60:61], v[106:107], v[16:17] op_sel_hi:[0,1,1]
	v_pk_fma_f32 v[34:35], v[104:105], v[70:71], v[34:35] op_sel_hi:[1,0,1]
	v_pk_fma_f32 v[36:37], v[106:107], v[70:71], v[36:37] op_sel_hi:[1,0,1]
	v_pk_fma_f32 v[30:31], v[104:105], v[62:63], v[30:31] op_sel_hi:[1,0,1]
	v_pk_fma_f32 v[32:33], v[106:107], v[62:63], v[32:33] op_sel_hi:[1,0,1]
	v_pk_fma_f32 v[26:27], v[104:105], v[72:73], v[26:27] op_sel_hi:[1,0,1]
	v_pk_fma_f32 v[28:29], v[106:107], v[72:73], v[28:29] op_sel_hi:[1,0,1]
	v_pk_fma_f32 v[22:23], v[104:105], v[64:65], v[22:23] op_sel_hi:[1,0,1]
	v_pk_fma_f32 v[24:25], v[106:107], v[64:65], v[24:25] op_sel_hi:[1,0,1]
	v_pk_fma_f32 v[18:19], v[104:105], v[74:75], v[18:19] op_sel_hi:[1,0,1]
	v_pk_fma_f32 v[20:21], v[106:107], v[74:75], v[20:21] op_sel_hi:[1,0,1]
	v_pk_fma_f32 v[10:11], v[104:105], v[66:67], v[10:11] op_sel_hi:[1,0,1]
	v_pk_fma_f32 v[12:13], v[106:107], v[66:67], v[12:13] op_sel_hi:[1,0,1]
	v_pk_fma_f32 v[6:7], v[104:105], v[76:77], v[6:7] op_sel_hi:[1,0,1]
	v_pk_fma_f32 v[8:9], v[106:107], v[76:77], v[8:9] op_sel_hi:[1,0,1]
	s_waitcnt lgkmcnt(0)
	v_pk_fma_f32 v[2:3], v[104:105], v[68:69], v[2:3] op_sel_hi:[1,0,1]
	v_pk_fma_f32 v[4:5], v[106:107], v[68:69], v[4:5] op_sel_hi:[1,0,1]
	ds_read2st64_b32 v[60:61], v53 offset1:16
	ds_read2st64_b32 v[62:63], v53 offset0:32 offset1:48
	ds_read2st64_b32 v[64:65], v53 offset0:64 offset1:80
	ds_read2st64_b32 v[66:67], v53 offset0:96 offset1:112
	ds_read_b32 v68, v53 offset:32768
	s_waitcnt lgkmcnt(4)
	v_mov_b32_e32 v70, v61
	s_waitcnt lgkmcnt(3)
	v_mov_b32_e32 v72, v63
	s_waitcnt lgkmcnt(2)
	v_mov_b32_e32 v74, v65
	s_waitcnt lgkmcnt(1)
	v_mov_b32_e32 v76, v67
	v_add_u32_e32 v53, 0xe0, v53
	s_waitcnt vmcnt(10)
	v_pk_fma_f32 v[14:15], v[60:61], v[108:109], v[14:15] op_sel_hi:[0,1,1]
	v_pk_fma_f32 v[16:17], v[60:61], v[110:111], v[16:17] op_sel_hi:[0,1,1]
	v_pk_fma_f32 v[34:35], v[108:109], v[70:71], v[34:35] op_sel_hi:[1,0,1]
	v_pk_fma_f32 v[36:37], v[110:111], v[70:71], v[36:37] op_sel_hi:[1,0,1]
	v_pk_fma_f32 v[30:31], v[108:109], v[62:63], v[30:31] op_sel_hi:[1,0,1]
	v_pk_fma_f32 v[32:33], v[110:111], v[62:63], v[32:33] op_sel_hi:[1,0,1]
	v_pk_fma_f32 v[26:27], v[108:109], v[72:73], v[26:27] op_sel_hi:[1,0,1]
	v_pk_fma_f32 v[28:29], v[110:111], v[72:73], v[28:29] op_sel_hi:[1,0,1]
	v_pk_fma_f32 v[22:23], v[108:109], v[64:65], v[22:23] op_sel_hi:[1,0,1]
	v_pk_fma_f32 v[24:25], v[110:111], v[64:65], v[24:25] op_sel_hi:[1,0,1]
	v_pk_fma_f32 v[18:19], v[108:109], v[74:75], v[18:19] op_sel_hi:[1,0,1]
	v_pk_fma_f32 v[20:21], v[110:111], v[74:75], v[20:21] op_sel_hi:[1,0,1]
	v_pk_fma_f32 v[10:11], v[108:109], v[66:67], v[10:11] op_sel_hi:[1,0,1]
	v_pk_fma_f32 v[12:13], v[110:111], v[66:67], v[12:13] op_sel_hi:[1,0,1]
	v_pk_fma_f32 v[6:7], v[108:109], v[76:77], v[6:7] op_sel_hi:[1,0,1]
	v_pk_fma_f32 v[8:9], v[110:111], v[76:77], v[8:9] op_sel_hi:[1,0,1]
	s_waitcnt lgkmcnt(0)
	v_pk_fma_f32 v[2:3], v[108:109], v[68:69], v[2:3] op_sel_hi:[1,0,1]
	v_pk_fma_f32 v[4:5], v[110:111], v[68:69], v[4:5] op_sel_hi:[1,0,1]
	ds_read2st64_b32 v[60:61], v53 offset1:16
	ds_read2st64_b32 v[62:63], v53 offset0:32 offset1:48
	ds_read2st64_b32 v[64:65], v53 offset0:64 offset1:80
	ds_read2st64_b32 v[66:67], v53 offset0:96 offset1:112
	ds_read_b32 v68, v53 offset:32768
	s_waitcnt lgkmcnt(4)
	v_mov_b32_e32 v70, v61
	s_waitcnt lgkmcnt(3)
	v_mov_b32_e32 v72, v63
	s_waitcnt lgkmcnt(2)
	v_mov_b32_e32 v74, v65
	s_waitcnt lgkmcnt(1)
	v_mov_b32_e32 v76, v67
	v_add_u32_e32 v53, 0xe0, v53
	s_waitcnt vmcnt(9)
	v_pk_fma_f32 v[14:15], v[60:61], v[112:113], v[14:15] op_sel_hi:[0,1,1]
	v_pk_fma_f32 v[16:17], v[60:61], v[114:115], v[16:17] op_sel_hi:[0,1,1]
	v_pk_fma_f32 v[34:35], v[112:113], v[70:71], v[34:35] op_sel_hi:[1,0,1]
	v_pk_fma_f32 v[36:37], v[114:115], v[70:71], v[36:37] op_sel_hi:[1,0,1]
	v_pk_fma_f32 v[30:31], v[112:113], v[62:63], v[30:31] op_sel_hi:[1,0,1]
	v_pk_fma_f32 v[32:33], v[114:115], v[62:63], v[32:33] op_sel_hi:[1,0,1]
	v_pk_fma_f32 v[26:27], v[112:113], v[72:73], v[26:27] op_sel_hi:[1,0,1]
	v_pk_fma_f32 v[28:29], v[114:115], v[72:73], v[28:29] op_sel_hi:[1,0,1]
	v_pk_fma_f32 v[22:23], v[112:113], v[64:65], v[22:23] op_sel_hi:[1,0,1]
	v_pk_fma_f32 v[24:25], v[114:115], v[64:65], v[24:25] op_sel_hi:[1,0,1]
	v_pk_fma_f32 v[18:19], v[112:113], v[74:75], v[18:19] op_sel_hi:[1,0,1]
	v_pk_fma_f32 v[20:21], v[114:115], v[74:75], v[20:21] op_sel_hi:[1,0,1]
	v_pk_fma_f32 v[10:11], v[112:113], v[66:67], v[10:11] op_sel_hi:[1,0,1]
	v_pk_fma_f32 v[12:13], v[114:115], v[66:67], v[12:13] op_sel_hi:[1,0,1]
	v_pk_fma_f32 v[6:7], v[112:113], v[76:77], v[6:7] op_sel_hi:[1,0,1]
	v_pk_fma_f32 v[8:9], v[114:115], v[76:77], v[8:9] op_sel_hi:[1,0,1]
	s_waitcnt lgkmcnt(0)
	v_pk_fma_f32 v[2:3], v[112:113], v[68:69], v[2:3] op_sel_hi:[1,0,1]
	v_pk_fma_f32 v[4:5], v[114:115], v[68:69], v[4:5] op_sel_hi:[1,0,1]
	ds_read2st64_b32 v[60:61], v53 offset1:16
	ds_read2st64_b32 v[62:63], v53 offset0:32 offset1:48
	ds_read2st64_b32 v[64:65], v53 offset0:64 offset1:80
	ds_read2st64_b32 v[66:67], v53 offset0:96 offset1:112
	ds_read_b32 v68, v53 offset:32768
	s_waitcnt lgkmcnt(4)
	v_mov_b32_e32 v70, v61
	s_waitcnt lgkmcnt(3)
	v_mov_b32_e32 v72, v63
	s_waitcnt lgkmcnt(2)
	v_mov_b32_e32 v74, v65
	s_waitcnt lgkmcnt(1)
	v_mov_b32_e32 v76, v67
	v_add_u32_e32 v53, 0xe0, v53
	s_waitcnt vmcnt(8)
	v_pk_fma_f32 v[14:15], v[60:61], v[116:117], v[14:15] op_sel_hi:[0,1,1]
	v_pk_fma_f32 v[16:17], v[60:61], v[118:119], v[16:17] op_sel_hi:[0,1,1]
	v_pk_fma_f32 v[34:35], v[116:117], v[70:71], v[34:35] op_sel_hi:[1,0,1]
	v_pk_fma_f32 v[36:37], v[118:119], v[70:71], v[36:37] op_sel_hi:[1,0,1]
	v_pk_fma_f32 v[30:31], v[116:117], v[62:63], v[30:31] op_sel_hi:[1,0,1]
	v_pk_fma_f32 v[32:33], v[118:119], v[62:63], v[32:33] op_sel_hi:[1,0,1]
	v_pk_fma_f32 v[26:27], v[116:117], v[72:73], v[26:27] op_sel_hi:[1,0,1]
	v_pk_fma_f32 v[28:29], v[118:119], v[72:73], v[28:29] op_sel_hi:[1,0,1]
	v_pk_fma_f32 v[22:23], v[116:117], v[64:65], v[22:23] op_sel_hi:[1,0,1]
	v_pk_fma_f32 v[24:25], v[118:119], v[64:65], v[24:25] op_sel_hi:[1,0,1]
	v_pk_fma_f32 v[18:19], v[116:117], v[74:75], v[18:19] op_sel_hi:[1,0,1]
	v_pk_fma_f32 v[20:21], v[118:119], v[74:75], v[20:21] op_sel_hi:[1,0,1]
	v_pk_fma_f32 v[10:11], v[116:117], v[66:67], v[10:11] op_sel_hi:[1,0,1]
	v_pk_fma_f32 v[12:13], v[118:119], v[66:67], v[12:13] op_sel_hi:[1,0,1]
	v_pk_fma_f32 v[6:7], v[116:117], v[76:77], v[6:7] op_sel_hi:[1,0,1]
	v_pk_fma_f32 v[8:9], v[118:119], v[76:77], v[8:9] op_sel_hi:[1,0,1]
	s_waitcnt lgkmcnt(0)
	v_pk_fma_f32 v[2:3], v[116:117], v[68:69], v[2:3] op_sel_hi:[1,0,1]
	v_pk_fma_f32 v[4:5], v[118:119], v[68:69], v[4:5] op_sel_hi:[1,0,1]
	ds_read2st64_b32 v[60:61], v53 offset1:16
	ds_read2st64_b32 v[62:63], v53 offset0:32 offset1:48
	ds_read2st64_b32 v[64:65], v53 offset0:64 offset1:80
	ds_read2st64_b32 v[66:67], v53 offset0:96 offset1:112
	ds_read_b32 v68, v53 offset:32768
	s_waitcnt lgkmcnt(4)
	v_mov_b32_e32 v70, v61
	s_waitcnt lgkmcnt(3)
	v_mov_b32_e32 v72, v63
	s_waitcnt lgkmcnt(2)
	v_mov_b32_e32 v74, v65
	s_waitcnt lgkmcnt(1)
	v_mov_b32_e32 v76, v67
	v_add_u32_e32 v53, 0xe0, v53
	s_waitcnt vmcnt(7)
	v_pk_fma_f32 v[14:15], v[60:61], v[120:121], v[14:15] op_sel_hi:[0,1,1]
	v_pk_fma_f32 v[16:17], v[60:61], v[122:123], v[16:17] op_sel_hi:[0,1,1]
	v_pk_fma_f32 v[34:35], v[120:121], v[70:71], v[34:35] op_sel_hi:[1,0,1]
	v_pk_fma_f32 v[36:37], v[122:123], v[70:71], v[36:37] op_sel_hi:[1,0,1]
	v_pk_fma_f32 v[30:31], v[120:121], v[62:63], v[30:31] op_sel_hi:[1,0,1]
	v_pk_fma_f32 v[32:33], v[122:123], v[62:63], v[32:33] op_sel_hi:[1,0,1]
	v_pk_fma_f32 v[26:27], v[120:121], v[72:73], v[26:27] op_sel_hi:[1,0,1]
	v_pk_fma_f32 v[28:29], v[122:123], v[72:73], v[28:29] op_sel_hi:[1,0,1]
	v_pk_fma_f32 v[22:23], v[120:121], v[64:65], v[22:23] op_sel_hi:[1,0,1]
	v_pk_fma_f32 v[24:25], v[122:123], v[64:65], v[24:25] op_sel_hi:[1,0,1]
	v_pk_fma_f32 v[18:19], v[120:121], v[74:75], v[18:19] op_sel_hi:[1,0,1]
	v_pk_fma_f32 v[20:21], v[122:123], v[74:75], v[20:21] op_sel_hi:[1,0,1]
	v_pk_fma_f32 v[10:11], v[120:121], v[66:67], v[10:11] op_sel_hi:[1,0,1]
	v_pk_fma_f32 v[12:13], v[122:123], v[66:67], v[12:13] op_sel_hi:[1,0,1]
	v_pk_fma_f32 v[6:7], v[120:121], v[76:77], v[6:7] op_sel_hi:[1,0,1]
	v_pk_fma_f32 v[8:9], v[122:123], v[76:77], v[8:9] op_sel_hi:[1,0,1]
	s_waitcnt lgkmcnt(0)
	v_pk_fma_f32 v[2:3], v[120:121], v[68:69], v[2:3] op_sel_hi:[1,0,1]
	v_pk_fma_f32 v[4:5], v[122:123], v[68:69], v[4:5] op_sel_hi:[1,0,1]
	ds_read2st64_b32 v[60:61], v53 offset1:16
	ds_read2st64_b32 v[62:63], v53 offset0:32 offset1:48
	ds_read2st64_b32 v[64:65], v53 offset0:64 offset1:80
	ds_read2st64_b32 v[66:67], v53 offset0:96 offset1:112
	ds_read_b32 v68, v53 offset:32768
	s_waitcnt lgkmcnt(4)
	v_mov_b32_e32 v70, v61
	s_waitcnt lgkmcnt(3)
	v_mov_b32_e32 v72, v63
	s_waitcnt lgkmcnt(2)
	v_mov_b32_e32 v74, v65
	s_waitcnt lgkmcnt(1)
	v_mov_b32_e32 v76, v67
	v_add_u32_e32 v53, 0xe0, v53
	s_waitcnt vmcnt(6)
	v_pk_fma_f32 v[14:15], v[60:61], v[124:125], v[14:15] op_sel_hi:[0,1,1]
	v_pk_fma_f32 v[16:17], v[60:61], v[126:127], v[16:17] op_sel_hi:[0,1,1]
	v_pk_fma_f32 v[34:35], v[124:125], v[70:71], v[34:35] op_sel_hi:[1,0,1]
	v_pk_fma_f32 v[36:37], v[126:127], v[70:71], v[36:37] op_sel_hi:[1,0,1]
	v_pk_fma_f32 v[30:31], v[124:125], v[62:63], v[30:31] op_sel_hi:[1,0,1]
	v_pk_fma_f32 v[32:33], v[126:127], v[62:63], v[32:33] op_sel_hi:[1,0,1]
	v_pk_fma_f32 v[26:27], v[124:125], v[72:73], v[26:27] op_sel_hi:[1,0,1]
	v_pk_fma_f32 v[28:29], v[126:127], v[72:73], v[28:29] op_sel_hi:[1,0,1]
	v_pk_fma_f32 v[22:23], v[124:125], v[64:65], v[22:23] op_sel_hi:[1,0,1]
	v_pk_fma_f32 v[24:25], v[126:127], v[64:65], v[24:25] op_sel_hi:[1,0,1]
	v_pk_fma_f32 v[18:19], v[124:125], v[74:75], v[18:19] op_sel_hi:[1,0,1]
	v_pk_fma_f32 v[20:21], v[126:127], v[74:75], v[20:21] op_sel_hi:[1,0,1]
	v_pk_fma_f32 v[10:11], v[124:125], v[66:67], v[10:11] op_sel_hi:[1,0,1]
	v_pk_fma_f32 v[12:13], v[126:127], v[66:67], v[12:13] op_sel_hi:[1,0,1]
	v_pk_fma_f32 v[6:7], v[124:125], v[76:77], v[6:7] op_sel_hi:[1,0,1]
	v_pk_fma_f32 v[8:9], v[126:127], v[76:77], v[8:9] op_sel_hi:[1,0,1]
	s_waitcnt lgkmcnt(0)
	v_pk_fma_f32 v[2:3], v[124:125], v[68:69], v[2:3] op_sel_hi:[1,0,1]
	v_pk_fma_f32 v[4:5], v[126:127], v[68:69], v[4:5] op_sel_hi:[1,0,1]
	ds_read2st64_b32 v[60:61], v53 offset1:16
	ds_read2st64_b32 v[62:63], v53 offset0:32 offset1:48
	ds_read2st64_b32 v[64:65], v53 offset0:64 offset1:80
	ds_read2st64_b32 v[66:67], v53 offset0:96 offset1:112
	ds_read_b32 v68, v53 offset:32768
	s_waitcnt lgkmcnt(4)
	v_mov_b32_e32 v70, v61
	s_waitcnt lgkmcnt(3)
	v_mov_b32_e32 v72, v63
	s_waitcnt lgkmcnt(2)
	v_mov_b32_e32 v74, v65
	s_waitcnt lgkmcnt(1)
	v_mov_b32_e32 v76, v67
	v_add_u32_e32 v53, 0xe0, v53
	s_waitcnt vmcnt(5)
	v_pk_fma_f32 v[14:15], v[60:61], v[128:129], v[14:15] op_sel_hi:[0,1,1]
	v_pk_fma_f32 v[16:17], v[60:61], v[130:131], v[16:17] op_sel_hi:[0,1,1]
	v_pk_fma_f32 v[34:35], v[128:129], v[70:71], v[34:35] op_sel_hi:[1,0,1]
	v_pk_fma_f32 v[36:37], v[130:131], v[70:71], v[36:37] op_sel_hi:[1,0,1]
	v_pk_fma_f32 v[30:31], v[128:129], v[62:63], v[30:31] op_sel_hi:[1,0,1]
	v_pk_fma_f32 v[32:33], v[130:131], v[62:63], v[32:33] op_sel_hi:[1,0,1]
	v_pk_fma_f32 v[26:27], v[128:129], v[72:73], v[26:27] op_sel_hi:[1,0,1]
	v_pk_fma_f32 v[28:29], v[130:131], v[72:73], v[28:29] op_sel_hi:[1,0,1]
	v_pk_fma_f32 v[22:23], v[128:129], v[64:65], v[22:23] op_sel_hi:[1,0,1]
	v_pk_fma_f32 v[24:25], v[130:131], v[64:65], v[24:25] op_sel_hi:[1,0,1]
	v_pk_fma_f32 v[18:19], v[128:129], v[74:75], v[18:19] op_sel_hi:[1,0,1]
	v_pk_fma_f32 v[20:21], v[130:131], v[74:75], v[20:21] op_sel_hi:[1,0,1]
	v_pk_fma_f32 v[10:11], v[128:129], v[66:67], v[10:11] op_sel_hi:[1,0,1]
	v_pk_fma_f32 v[12:13], v[130:131], v[66:67], v[12:13] op_sel_hi:[1,0,1]
	v_pk_fma_f32 v[6:7], v[128:129], v[76:77], v[6:7] op_sel_hi:[1,0,1]
	v_pk_fma_f32 v[8:9], v[130:131], v[76:77], v[8:9] op_sel_hi:[1,0,1]
	s_waitcnt lgkmcnt(0)
	v_pk_fma_f32 v[2:3], v[128:129], v[68:69], v[2:3] op_sel_hi:[1,0,1]
	v_pk_fma_f32 v[4:5], v[130:131], v[68:69], v[4:5] op_sel_hi:[1,0,1]
	ds_read2st64_b32 v[60:61], v53 offset1:16
	ds_read2st64_b32 v[62:63], v53 offset0:32 offset1:48
	ds_read2st64_b32 v[64:65], v53 offset0:64 offset1:80
	ds_read2st64_b32 v[66:67], v53 offset0:96 offset1:112
	ds_read_b32 v68, v53 offset:32768
	s_waitcnt lgkmcnt(4)
	v_mov_b32_e32 v70, v61
	s_waitcnt lgkmcnt(3)
	v_mov_b32_e32 v72, v63
	s_waitcnt lgkmcnt(2)
	v_mov_b32_e32 v74, v65
	s_waitcnt lgkmcnt(1)
	v_mov_b32_e32 v76, v67
	v_add_u32_e32 v53, 0xe0, v53
	s_waitcnt vmcnt(4)
	v_pk_fma_f32 v[14:15], v[60:61], v[132:133], v[14:15] op_sel_hi:[0,1,1]
	v_pk_fma_f32 v[16:17], v[60:61], v[134:135], v[16:17] op_sel_hi:[0,1,1]
	v_pk_fma_f32 v[34:35], v[132:133], v[70:71], v[34:35] op_sel_hi:[1,0,1]
	v_pk_fma_f32 v[36:37], v[134:135], v[70:71], v[36:37] op_sel_hi:[1,0,1]
	v_pk_fma_f32 v[30:31], v[132:133], v[62:63], v[30:31] op_sel_hi:[1,0,1]
	v_pk_fma_f32 v[32:33], v[134:135], v[62:63], v[32:33] op_sel_hi:[1,0,1]
	v_pk_fma_f32 v[26:27], v[132:133], v[72:73], v[26:27] op_sel_hi:[1,0,1]
	v_pk_fma_f32 v[28:29], v[134:135], v[72:73], v[28:29] op_sel_hi:[1,0,1]
	v_pk_fma_f32 v[22:23], v[132:133], v[64:65], v[22:23] op_sel_hi:[1,0,1]
	v_pk_fma_f32 v[24:25], v[134:135], v[64:65], v[24:25] op_sel_hi:[1,0,1]
	v_pk_fma_f32 v[18:19], v[132:133], v[74:75], v[18:19] op_sel_hi:[1,0,1]
	v_pk_fma_f32 v[20:21], v[134:135], v[74:75], v[20:21] op_sel_hi:[1,0,1]
	v_pk_fma_f32 v[10:11], v[132:133], v[66:67], v[10:11] op_sel_hi:[1,0,1]
	v_pk_fma_f32 v[12:13], v[134:135], v[66:67], v[12:13] op_sel_hi:[1,0,1]
	v_pk_fma_f32 v[6:7], v[132:133], v[76:77], v[6:7] op_sel_hi:[1,0,1]
	v_pk_fma_f32 v[8:9], v[134:135], v[76:77], v[8:9] op_sel_hi:[1,0,1]
	s_waitcnt lgkmcnt(0)
	v_pk_fma_f32 v[2:3], v[132:133], v[68:69], v[2:3] op_sel_hi:[1,0,1]
	v_pk_fma_f32 v[4:5], v[134:135], v[68:69], v[4:5] op_sel_hi:[1,0,1]
	ds_read2st64_b32 v[60:61], v53 offset1:16
	ds_read2st64_b32 v[62:63], v53 offset0:32 offset1:48
	ds_read2st64_b32 v[64:65], v53 offset0:64 offset1:80
	ds_read2st64_b32 v[66:67], v53 offset0:96 offset1:112
	ds_read_b32 v68, v53 offset:32768
	s_waitcnt lgkmcnt(4)
	v_mov_b32_e32 v70, v61
	s_waitcnt lgkmcnt(3)
	v_mov_b32_e32 v72, v63
	s_waitcnt lgkmcnt(2)
	v_mov_b32_e32 v74, v65
	s_waitcnt lgkmcnt(1)
	v_mov_b32_e32 v76, v67
	v_add_u32_e32 v53, 0xe0, v53
	s_waitcnt vmcnt(3)
	v_pk_fma_f32 v[14:15], v[60:61], v[136:137], v[14:15] op_sel_hi:[0,1,1]
	v_pk_fma_f32 v[16:17], v[60:61], v[138:139], v[16:17] op_sel_hi:[0,1,1]
	v_pk_fma_f32 v[34:35], v[136:137], v[70:71], v[34:35] op_sel_hi:[1,0,1]
	v_pk_fma_f32 v[36:37], v[138:139], v[70:71], v[36:37] op_sel_hi:[1,0,1]
	v_pk_fma_f32 v[30:31], v[136:137], v[62:63], v[30:31] op_sel_hi:[1,0,1]
	v_pk_fma_f32 v[32:33], v[138:139], v[62:63], v[32:33] op_sel_hi:[1,0,1]
	v_pk_fma_f32 v[26:27], v[136:137], v[72:73], v[26:27] op_sel_hi:[1,0,1]
	v_pk_fma_f32 v[28:29], v[138:139], v[72:73], v[28:29] op_sel_hi:[1,0,1]
	v_pk_fma_f32 v[22:23], v[136:137], v[64:65], v[22:23] op_sel_hi:[1,0,1]
	v_pk_fma_f32 v[24:25], v[138:139], v[64:65], v[24:25] op_sel_hi:[1,0,1]
	v_pk_fma_f32 v[18:19], v[136:137], v[74:75], v[18:19] op_sel_hi:[1,0,1]
	v_pk_fma_f32 v[20:21], v[138:139], v[74:75], v[20:21] op_sel_hi:[1,0,1]
	v_pk_fma_f32 v[10:11], v[136:137], v[66:67], v[10:11] op_sel_hi:[1,0,1]
	v_pk_fma_f32 v[12:13], v[138:139], v[66:67], v[12:13] op_sel_hi:[1,0,1]
	v_pk_fma_f32 v[6:7], v[136:137], v[76:77], v[6:7] op_sel_hi:[1,0,1]
	v_pk_fma_f32 v[8:9], v[138:139], v[76:77], v[8:9] op_sel_hi:[1,0,1]
	s_waitcnt lgkmcnt(0)
	v_pk_fma_f32 v[2:3], v[136:137], v[68:69], v[2:3] op_sel_hi:[1,0,1]
	v_pk_fma_f32 v[4:5], v[138:139], v[68:69], v[4:5] op_sel_hi:[1,0,1]
	ds_read2st64_b32 v[60:61], v53 offset1:16
	ds_read2st64_b32 v[62:63], v53 offset0:32 offset1:48
	ds_read2st64_b32 v[64:65], v53 offset0:64 offset1:80
	ds_read2st64_b32 v[66:67], v53 offset0:96 offset1:112
	ds_read_b32 v68, v53 offset:32768
	s_waitcnt lgkmcnt(4)
	v_mov_b32_e32 v70, v61
	s_waitcnt lgkmcnt(3)
	v_mov_b32_e32 v72, v63
	s_waitcnt lgkmcnt(2)
	v_mov_b32_e32 v74, v65
	s_waitcnt lgkmcnt(1)
	v_mov_b32_e32 v76, v67
	v_add_u32_e32 v53, 0xe0, v53
	s_waitcnt vmcnt(2)
	v_pk_fma_f32 v[14:15], v[60:61], v[140:141], v[14:15] op_sel_hi:[0,1,1]
	v_pk_fma_f32 v[16:17], v[60:61], v[142:143], v[16:17] op_sel_hi:[0,1,1]
	v_pk_fma_f32 v[34:35], v[140:141], v[70:71], v[34:35] op_sel_hi:[1,0,1]
	v_pk_fma_f32 v[36:37], v[142:143], v[70:71], v[36:37] op_sel_hi:[1,0,1]
	v_pk_fma_f32 v[30:31], v[140:141], v[62:63], v[30:31] op_sel_hi:[1,0,1]
	v_pk_fma_f32 v[32:33], v[142:143], v[62:63], v[32:33] op_sel_hi:[1,0,1]
	v_pk_fma_f32 v[26:27], v[140:141], v[72:73], v[26:27] op_sel_hi:[1,0,1]
	v_pk_fma_f32 v[28:29], v[142:143], v[72:73], v[28:29] op_sel_hi:[1,0,1]
	v_pk_fma_f32 v[22:23], v[140:141], v[64:65], v[22:23] op_sel_hi:[1,0,1]
	v_pk_fma_f32 v[24:25], v[142:143], v[64:65], v[24:25] op_sel_hi:[1,0,1]
	v_pk_fma_f32 v[18:19], v[140:141], v[74:75], v[18:19] op_sel_hi:[1,0,1]
	v_pk_fma_f32 v[20:21], v[142:143], v[74:75], v[20:21] op_sel_hi:[1,0,1]
	v_pk_fma_f32 v[10:11], v[140:141], v[66:67], v[10:11] op_sel_hi:[1,0,1]
	v_pk_fma_f32 v[12:13], v[142:143], v[66:67], v[12:13] op_sel_hi:[1,0,1]
	v_pk_fma_f32 v[6:7], v[140:141], v[76:77], v[6:7] op_sel_hi:[1,0,1]
	v_pk_fma_f32 v[8:9], v[142:143], v[76:77], v[8:9] op_sel_hi:[1,0,1]
	s_waitcnt lgkmcnt(0)
	v_pk_fma_f32 v[2:3], v[140:141], v[68:69], v[2:3] op_sel_hi:[1,0,1]
	v_pk_fma_f32 v[4:5], v[142:143], v[68:69], v[4:5] op_sel_hi:[1,0,1]
	ds_read2st64_b32 v[60:61], v53 offset1:16
	ds_read2st64_b32 v[62:63], v53 offset0:32 offset1:48
	ds_read2st64_b32 v[64:65], v53 offset0:64 offset1:80
	ds_read2st64_b32 v[66:67], v53 offset0:96 offset1:112
	ds_read_b32 v68, v53 offset:32768
	s_waitcnt lgkmcnt(4)
	v_mov_b32_e32 v70, v61
	s_waitcnt lgkmcnt(3)
	v_mov_b32_e32 v72, v63
	s_waitcnt lgkmcnt(2)
	v_mov_b32_e32 v74, v65
	s_waitcnt lgkmcnt(1)
	v_mov_b32_e32 v76, v67
	v_add_u32_e32 v53, 0xe0, v53
	s_waitcnt vmcnt(1)
	v_pk_fma_f32 v[14:15], v[60:61], v[148:149], v[14:15] op_sel_hi:[0,1,1]
	v_pk_fma_f32 v[16:17], v[60:61], v[150:151], v[16:17] op_sel_hi:[0,1,1]
	v_pk_fma_f32 v[34:35], v[148:149], v[70:71], v[34:35] op_sel_hi:[1,0,1]
	v_pk_fma_f32 v[36:37], v[150:151], v[70:71], v[36:37] op_sel_hi:[1,0,1]
	v_pk_fma_f32 v[30:31], v[148:149], v[62:63], v[30:31] op_sel_hi:[1,0,1]
	v_pk_fma_f32 v[32:33], v[150:151], v[62:63], v[32:33] op_sel_hi:[1,0,1]
	v_pk_fma_f32 v[26:27], v[148:149], v[72:73], v[26:27] op_sel_hi:[1,0,1]
	v_pk_fma_f32 v[28:29], v[150:151], v[72:73], v[28:29] op_sel_hi:[1,0,1]
	v_pk_fma_f32 v[22:23], v[148:149], v[64:65], v[22:23] op_sel_hi:[1,0,1]
	v_pk_fma_f32 v[24:25], v[150:151], v[64:65], v[24:25] op_sel_hi:[1,0,1]
	v_pk_fma_f32 v[18:19], v[148:149], v[74:75], v[18:19] op_sel_hi:[1,0,1]
	v_pk_fma_f32 v[20:21], v[150:151], v[74:75], v[20:21] op_sel_hi:[1,0,1]
	v_pk_fma_f32 v[10:11], v[148:149], v[66:67], v[10:11] op_sel_hi:[1,0,1]
	v_pk_fma_f32 v[12:13], v[150:151], v[66:67], v[12:13] op_sel_hi:[1,0,1]
	v_pk_fma_f32 v[6:7], v[148:149], v[76:77], v[6:7] op_sel_hi:[1,0,1]
	v_pk_fma_f32 v[8:9], v[150:151], v[76:77], v[8:9] op_sel_hi:[1,0,1]
	s_waitcnt lgkmcnt(0)
	v_pk_fma_f32 v[2:3], v[148:149], v[68:69], v[2:3] op_sel_hi:[1,0,1]
	v_pk_fma_f32 v[4:5], v[150:151], v[68:69], v[4:5] op_sel_hi:[1,0,1]
	ds_read2st64_b32 v[60:61], v53 offset1:16
	ds_read2st64_b32 v[62:63], v53 offset0:32 offset1:48
	ds_read2st64_b32 v[64:65], v53 offset0:64 offset1:80
	ds_read2st64_b32 v[66:67], v53 offset0:96 offset1:112
	ds_read_b32 v68, v53 offset:32768
	s_waitcnt lgkmcnt(4)
	v_mov_b32_e32 v70, v61
	s_waitcnt lgkmcnt(3)
	v_mov_b32_e32 v72, v63
	s_waitcnt lgkmcnt(2)
	v_mov_b32_e32 v74, v65
	s_waitcnt lgkmcnt(1)
	v_mov_b32_e32 v76, v67
	v_add_u32_e32 v53, 0xe0, v53
	s_waitcnt vmcnt(0)
	v_pk_fma_f32 v[14:15], v[60:61], v[152:153], v[14:15] op_sel_hi:[0,1,1]
	v_pk_fma_f32 v[16:17], v[60:61], v[154:155], v[16:17] op_sel_hi:[0,1,1]
	v_pk_fma_f32 v[34:35], v[152:153], v[70:71], v[34:35] op_sel_hi:[1,0,1]
	v_pk_fma_f32 v[36:37], v[154:155], v[70:71], v[36:37] op_sel_hi:[1,0,1]
	v_pk_fma_f32 v[30:31], v[152:153], v[62:63], v[30:31] op_sel_hi:[1,0,1]
	v_pk_fma_f32 v[32:33], v[154:155], v[62:63], v[32:33] op_sel_hi:[1,0,1]
	v_pk_fma_f32 v[26:27], v[152:153], v[72:73], v[26:27] op_sel_hi:[1,0,1]
	v_pk_fma_f32 v[28:29], v[154:155], v[72:73], v[28:29] op_sel_hi:[1,0,1]
	v_pk_fma_f32 v[22:23], v[152:153], v[64:65], v[22:23] op_sel_hi:[1,0,1]
	v_pk_fma_f32 v[24:25], v[154:155], v[64:65], v[24:25] op_sel_hi:[1,0,1]
	v_pk_fma_f32 v[18:19], v[152:153], v[74:75], v[18:19] op_sel_hi:[1,0,1]
	v_pk_fma_f32 v[20:21], v[154:155], v[74:75], v[20:21] op_sel_hi:[1,0,1]
	v_pk_fma_f32 v[10:11], v[152:153], v[66:67], v[10:11] op_sel_hi:[1,0,1]
	v_pk_fma_f32 v[12:13], v[154:155], v[66:67], v[12:13] op_sel_hi:[1,0,1]
	v_pk_fma_f32 v[6:7], v[152:153], v[76:77], v[6:7] op_sel_hi:[1,0,1]
	v_pk_fma_f32 v[8:9], v[154:155], v[76:77], v[8:9] op_sel_hi:[1,0,1]
	s_waitcnt lgkmcnt(0)
	v_pk_fma_f32 v[2:3], v[152:153], v[68:69], v[2:3] op_sel_hi:[1,0,1]
	v_pk_fma_f32 v[4:5], v[154:155], v[68:69], v[4:5] op_sel_hi:[1,0,1]
	s_and_saveexec_b64 s[14:15], s[0:1]
	ds_read2st64_b32 v[60:61], v53 offset1:16
	ds_read2st64_b32 v[62:63], v53 offset0:32 offset1:48
	ds_read2st64_b32 v[64:65], v53 offset0:64 offset1:80
	ds_read2st64_b32 v[66:67], v53 offset0:96 offset1:112
	ds_read_b32 v68, v53 offset:32768
	s_waitcnt lgkmcnt(4)
	v_mov_b32_e32 v70, v61
	s_waitcnt lgkmcnt(3)
	v_mov_b32_e32 v72, v63
	s_waitcnt lgkmcnt(2)
	v_mov_b32_e32 v74, v65
	s_waitcnt lgkmcnt(1)
	v_mov_b32_e32 v76, v67
	v_add_u32_e32 v53, 0xe0, v53
	s_waitcnt vmcnt(0)
	v_pk_fma_f32 v[14:15], v[60:61], v[156:157], v[14:15] op_sel_hi:[0,1,1]
	v_pk_fma_f32 v[16:17], v[60:61], v[158:159], v[16:17] op_sel_hi:[0,1,1]
	v_pk_fma_f32 v[34:35], v[156:157], v[70:71], v[34:35] op_sel_hi:[1,0,1]
	v_pk_fma_f32 v[36:37], v[158:159], v[70:71], v[36:37] op_sel_hi:[1,0,1]
	v_pk_fma_f32 v[30:31], v[156:157], v[62:63], v[30:31] op_sel_hi:[1,0,1]
	v_pk_fma_f32 v[32:33], v[158:159], v[62:63], v[32:33] op_sel_hi:[1,0,1]
	v_pk_fma_f32 v[26:27], v[156:157], v[72:73], v[26:27] op_sel_hi:[1,0,1]
	v_pk_fma_f32 v[28:29], v[158:159], v[72:73], v[28:29] op_sel_hi:[1,0,1]
	v_pk_fma_f32 v[22:23], v[156:157], v[64:65], v[22:23] op_sel_hi:[1,0,1]
	v_pk_fma_f32 v[24:25], v[158:159], v[64:65], v[24:25] op_sel_hi:[1,0,1]
	v_pk_fma_f32 v[18:19], v[156:157], v[74:75], v[18:19] op_sel_hi:[1,0,1]
	v_pk_fma_f32 v[20:21], v[158:159], v[74:75], v[20:21] op_sel_hi:[1,0,1]
	v_pk_fma_f32 v[10:11], v[156:157], v[66:67], v[10:11] op_sel_hi:[1,0,1]
	v_pk_fma_f32 v[12:13], v[158:159], v[66:67], v[12:13] op_sel_hi:[1,0,1]
	v_pk_fma_f32 v[6:7], v[156:157], v[76:77], v[6:7] op_sel_hi:[1,0,1]
	v_pk_fma_f32 v[8:9], v[158:159], v[76:77], v[8:9] op_sel_hi:[1,0,1]
	s_waitcnt lgkmcnt(0)
	v_pk_fma_f32 v[2:3], v[156:157], v[68:69], v[2:3] op_sel_hi:[1,0,1]
	v_pk_fma_f32 v[4:5], v[158:159], v[68:69], v[4:5] op_sel_hi:[1,0,1]
	s_or_b64 exec, exec, s[14:15]
	ds_write_b128 v52, v[14:17] offset:36864
	ds_write_b128 v52, v[34:37] offset:36880
	ds_write_b128 v52, v[30:33] offset:36896
	ds_write_b128 v52, v[26:29] offset:36912
	ds_write_b128 v52, v[22:25] offset:36928
	ds_write_b128 v52, v[18:21] offset:36944
	ds_write_b128 v52, v[10:13] offset:36960
	ds_write_b128 v52, v[6:9] offset:36976
	ds_write_b128 v52, v[2:5] offset:36992
